# qk-prep rows: norm-weight pointers preloaded once per item (removes one dependent kernarg round trip per row); raw/weight/rope loads now in flight together
# speedup vs baseline: 1.0167x; 1.0013x over previous
.LBB0_338:
	s_or_saveexec_b64 s[28:29], s[24:25]
	s_waitcnt lgkmcnt(0)
	v_mov_b64_e32 v[2:3], s[20:21]
	v_mov_b64_e32 v[4:5], s[30:31]
	s_xor_b64 exec, exec, s[28:29]
	s_cbranch_execz .LBB0_351
	v_and_b32_e32 v3, 7, v152
	v_readlane_b32 s24, v253, 34
	v_lshlrev_b32_e32 v0, 4, v3
	v_readlane_b32 s25, v253, 35
	s_lshl_b32 s21, s5, 1
	v_bfe_u32 v6, v152, 3, 3
	v_lshl_add_u64 v[14:15], s[24:25], 0, v[0:1]
	v_readlane_b32 s24, v255, 2
	v_readlane_b32 s25, v255, 3
	s_add_i32 s24, s21, s24
	s_ashr_i32 s25, s24, 31
	s_lshl_b64 s[24:25], s[24:25], 8
	s_ashr_i32 s21, s20, 31
	s_add_u32 s46, s24, s20
	v_lshl_or_b32 v7, s5, 3, v6
	v_mov_b64_e32 v[4:5], s[20:21]
	s_movk_i32 s24, 0x1100
	s_addc_u32 s47, s25, s21
	v_mad_u64_u32 v[16:17], s[24:25], v7, s24, v[4:5]
	v_readlane_b32 s24, v252, 30
	v_readlane_b32 s25, v252, 31
	v_lshlrev_b32_e32 v4, 7, v6
	v_mov_b32_e32 v5, v1
	v_lshl_add_u64 v[18:19], s[24:25], 0, v[0:1]
	v_readlane_b32 s24, v252, 28
	v_readlane_b32 s25, v252, 29
	v_readlane_b32 s52, v254, 42
	v_lshl_add_u64 v[12:13], s[88:89], 0, v[0:1]
	v_lshl_add_u64 v[4:5], s[24:25], 0, v[4:5]
	v_lshl_add_u64 v[20:21], v[4:5], 0, v[0:1]
	v_lshlrev_b32_e32 v0, 8, v6
	v_readlane_b32 s53, v254, 43
	v_lshlrev_b32_e32 v2, 6, v6
	v_lshlrev_b32_e32 v10, 3, v3
	v_lshl_add_u64 v[4:5], s[52:53], 0, v[0:1]
	v_lshlrev_b32_e32 v0, 5, v3
	v_lshl_add_u64 v[22:23], v[4:5], 0, v[0:1]
	v_lshlrev_b32_e32 v32, 3, v11
	s_mov_b64 s[30:31], 0
	v_lshlrev_b32_e32 v0, 1, v2
	s_mov_b32 s52, 0x3e38aa3b
	s_movk_i32 s53, 0x7b
	v_readlane_b32 s54, v254, 44
	v_readlane_b32 s55, v254, 45
	v_readlane_b32 s56, v254, 46
	v_readlane_b32 s57, v254, 47
	v_readlane_b32 s58, v254, 48
	v_readlane_b32 s59, v254, 49
	v_readlane_b32 s60, v254, 50
	v_readlane_b32 s61, v254, 51
	v_readlane_b32 s62, v254, 52
	v_readlane_b32 s63, v254, 53
	v_readlane_b32 s64, v254, 54
	v_readlane_b32 s65, v254, 55
	v_readlane_b32 s66, v254, 56
	v_readlane_b32 s67, v254, 57
	v_mov_b32_e32 v56, v203
	v_mov_b32_e32 v57, v1
	v_lshl_add_u64 v[56:57], s[0:1], 0, v[56:57]
	global_load_dwordx2 v[52:53], v[56:57], off
	v_mov_b32_e32 v56, v202
	v_mov_b32_e32 v57, v1
	v_lshl_add_u64 v[56:57], s[0:1], 0, v[56:57]
	global_load_dwordx2 v[54:55], v[56:57], off
	s_waitcnt vmcnt(0)
	s_branch .LBB0_341

.LBB0_341:
	v_cmp_gt_u32_e64 s[44:45], 64, v11
	s_and_b64 s[24:25], s[96:97], s[44:45]
	v_cmp_lt_u32_e64 s[42:43], 63, v11
	s_xor_b64 s[34:35], s[24:25], -1
	s_and_saveexec_b64 s[24:25], s[34:35]
	s_cbranch_execz .LBB0_340
	v_and_b32_e32 v24, 63, v11
	s_andn2_b64 vcc, exec, s[26:27]
	s_mov_b64 s[34:35], -1
	s_cbranch_vccnz .LBB0_346
	v_cndmask_b32_e64 v6, v54, v52, s[44:45]
	v_cndmask_b32_e64 v7, v55, v53, s[44:45]
	v_readlane_b32 s34, v252, 36
	v_readlane_b32 s35, v252, 37
	v_or_b32_e32 v25, s75, v24
	v_and_b32_e32 v4, 0xfffffe00, v32
	v_mov_b64_e32 v[2:3], s[34:35]
	s_movk_i32 s34, 0xc00
	v_mad_u64_u32 v[2:3], s[34:35], v25, s34, v[2:3]
	v_ashrrev_i32_e32 v5, 31, v4
	v_lshl_add_u64 v[2:3], v[4:5], 1, v[2:3]
	v_lshlrev_b32_e32 v8, 1, v10
	v_mov_b32_e32 v9, v1
	v_lshl_add_u64 v[2:3], v[2:3], 0, v[0:1]
	v_lshl_add_u64 v[2:3], v[2:3], 0, v[8:9]
	global_load_dwordx4 v[2:5], v[2:3], off
	v_lshlrev_b32_e32 v8, 2, v10
	v_lshlrev_b32_e32 v25, 7, v25
	v_mov_b32_e32 v31, v1
	v_and_b32_e32 v30, 0x7ff80, v25
	v_lshl_add_u64 v[38:39], v[12:13], 0, v[30:31]
	v_lshl_add_u64 v[30:31], v[14:15], 0, v[30:31]
	v_cmp_lt_i32_e32 vcc, v227, v221
	s_nop 0
	v_lshl_add_u64 v[6:7], s[40:41], 2, v[6:7]
	v_lshl_add_u64 v[26:27], v[6:7], 0, v[8:9]
	global_load_dwordx4 v[6:9], v[26:27], off offset:16
	s_nop 0
	global_load_dwordx4 v[26:29], v[26:27], off
	s_nop 0
	global_load_dwordx4 v[34:37], v[30:31], off
	s_nop 0
	global_load_dwordx4 v[38:41], v[38:39], off
	s_waitcnt vmcnt(4)
	v_cndmask_b32_e32 v25, v220, v227, vcc
	v_lshlrev_b32_e32 v25, 2, v25
	v_cmp_lt_i32_e32 vcc, v226, v221
	v_lshlrev_b32_e32 v30, 16, v2
	v_and_b32_e32 v31, 0xffff0000, v2
	v_lshlrev_b32_e32 v2, 16, v3
	v_and_b32_e32 v3, 0xffff0000, v3
	v_pk_mul_f32 v[46:47], v[30:31], v[30:31]
	v_pk_mul_f32 v[48:49], v[2:3], v[2:3]
	v_add_f32_e32 v33, v46, v47
	v_lshlrev_b32_e32 v42, 16, v4
	v_and_b32_e32 v43, 0xffff0000, v4
	v_add_f32_e32 v33, v33, v48
	v_pk_mul_f32 v[50:51], v[42:43], v[42:43]
	v_add_f32_e32 v33, v49, v33
	v_lshlrev_b32_e32 v4, 16, v5
	v_and_b32_e32 v5, 0xffff0000, v5
	v_add_f32_e32 v33, v50, v33
	v_pk_mul_f32 v[44:45], v[4:5], v[4:5]
	v_add_f32_e32 v33, v51, v33
	v_add_f32_e32 v33, v44, v33
	v_add_f32_e32 v33, v45, v33
	ds_bpermute_b32 v25, v25, v33
	v_cndmask_b32_e32 v44, v220, v226, vcc
	v_lshlrev_b32_e32 v44, 2, v44
	v_cmp_lt_i32_e32 vcc, v235, v221
	s_waitcnt lgkmcnt(0)
	v_add_f32_e32 v25, v33, v25
	ds_bpermute_b32 v33, v44, v25
	v_cndmask_b32_e32 v44, v220, v235, vcc
	v_lshlrev_b32_e32 v44, 2, v44
	s_waitcnt lgkmcnt(0)
	v_add_f32_e32 v25, v25, v33
	ds_bpermute_b32 v33, v44, v25
	s_waitcnt lgkmcnt(0)
	v_add_f32_e32 v25, v25, v33
	v_fmamk_f32 v25, v25, 0x3c800000, v187
	v_mul_f32_e32 v33, 0x4b800000, v25
	v_cmp_gt_f32_e32 vcc, s82, v25
	s_nop 1
	v_cndmask_b32_e32 v25, v25, v33, vcc
	v_rsq_f32_e32 v25, v25
	s_nop 0
	v_mul_f32_e32 v33, 0x45800000, v25
	v_cndmask_b32_e32 v44, v25, v33, vcc
	v_pk_mul_f32 v[30:31], v[44:45], v[30:31] op_sel_hi:[0,1]
	v_pk_mul_f32 v[2:3], v[44:45], v[2:3] op_sel_hi:[0,1]
	v_pk_mul_f32 v[42:43], v[44:45], v[42:43] op_sel_hi:[0,1]
	v_pk_mul_f32 v[4:5], v[44:45], v[4:5] op_sel_hi:[0,1]
	s_waitcnt vmcnt(2)
	v_pk_mul_f32 v[26:27], v[26:27], v[30:31]
	v_pk_mul_f32 v[28:29], v[28:29], v[2:3]
	v_pk_mul_f32 v[30:31], v[6:7], v[42:43]
	v_pk_mul_f32 v[42:43], v[8:9], v[4:5]
	s_waitcnt vmcnt(1)
	v_pk_mul_f32 v[44:45], v[34:35], v[26:27] op_sel:[0,1] op_sel_hi:[0,0]
	v_pk_mul_f32 v[6:7], v[34:35], v[28:29] op_sel:[1,1] op_sel_hi:[1,0]
	v_pk_mul_f32 v[8:9], v[30:31], v[36:37] op_sel:[1,0] op_sel_hi:[0,0]
	s_waitcnt vmcnt(0)
	v_pk_mul_f32 v[46:47], v[38:39], v[26:27] op_sel_hi:[0,1]
	v_mov_b32_e32 v36, v41
	v_mul_f32_e32 v34, v37, v43
	v_mul_f32_e32 v48, v41, v43
	v_pk_fma_f32 v[2:3], v[38:39], v[26:27], v[44:45] op_sel_hi:[0,1,1]
	v_pk_fma_f32 v[4:5], v[38:39], v[28:29], v[6:7] op_sel:[1,0,0] neg_lo:[0,0,1] neg_hi:[0,0,1]
	v_pk_fma_f32 v[26:27], v[38:39], v[28:29], v[6:7] op_sel:[1,0,0]
	v_pk_fma_f32 v[6:7], v[40:41], v[30:31], v[8:9] op_sel_hi:[0,1,1] neg_lo:[0,0,1] neg_hi:[0,0,1]
	v_pk_fma_f32 v[28:29], v[40:41], v[30:31], v[8:9] op_sel_hi:[0,1,1]
	v_mov_b32_e32 v40, v37
	v_pk_fma_f32 v[8:9], v[36:37], v[42:43], v[34:35] op_sel_hi:[1,1,0] neg_lo:[0,0,1] neg_hi:[0,0,1]
	v_pk_fma_f32 v[30:31], v[40:41], v[42:43], v[48:49] op_sel_hi:[1,1,0]
	v_sub_f32_e32 v2, v46, v44
	s_cbranch_execz .LBB0_347

.LBB0_442:
	s_or_saveexec_b64 s[96:97], s[30:31]
	v_mov_b64_e32 v[2:3], s[24:25]
	v_mov_b64_e32 v[4:5], s[26:27]
	v_mov_b64_e32 v[14:15], s[28:29]
	s_xor_b64 exec, exec, s[96:97]
	s_cbranch_execz .LBB0_455
	s_lshl_b32 s24, s94, 1
	v_readlane_b32 s14, v255, 2
	s_add_i32 s24, s24, s14
	s_ashr_i32 s25, s24, 31
	v_bfe_u32 v3, v152, 3, 3
	v_lshlrev_b32_e32 v0, 3, v152
	s_lshl_b64 s[28:29], s[24:25], 8
	s_ashr_i32 s27, s26, 31
	v_and_b32_e32 v10, 56, v0
	s_add_u32 s30, s28, s26
	v_lshl_or_b32 v0, s94, 3, v3
	s_addc_u32 s31, s29, s27
	v_lshlrev_b64 v[4:5], 8, v[0:1]
	s_lshl_b64 s[46:47], s[24:25], 19
	v_readlane_b32 s24, v252, 28
	v_lshl_add_u64 v[12:13], v[4:5], 0, s[26:27]
	v_readlane_b32 s28, v252, 30
	v_lshlrev_b32_e32 v4, 7, v3
	v_mov_b32_e32 v5, v1
	v_readlane_b32 s25, v252, 29
	v_lshlrev_b32_e32 v0, 1, v10
	v_readlane_b32 s29, v252, 31
	v_lshl_add_u64 v[4:5], s[24:25], 0, v[4:5]
	v_readlane_b32 s52, v254, 42
	v_readlane_b32 s24, v253, 38
	v_lshl_add_u64 v[14:15], s[28:29], 0, v[0:1]
	v_lshl_add_u64 v[16:17], v[4:5], 0, v[0:1]
	v_lshlrev_b32_e32 v0, 8, v3
	v_readlane_b32 s53, v254, 43
	s_add_u32 s24, s24, s46
	v_readlane_b32 s25, v253, 39
	v_lshl_add_u64 v[4:5], s[52:53], 0, v[0:1]
	v_lshlrev_b32_e32 v6, 2, v10
	v_mov_b32_e32 v7, v1
	s_addc_u32 s25, s25, s47
	v_lshlrev_b32_e32 v2, 6, v3
	v_lshl_add_u64 v[18:19], v[4:5], 0, v[6:7]
	v_lshl_add_u64 v[4:5], s[24:25], 0, v[0:1]
	v_lshl_add_u64 v[20:21], v[4:5], 0, v[6:7]
	v_lshlrev_b32_e32 v24, 3, v11
	s_mov_b64 s[24:25], 0
	v_lshlrev_b32_e32 v0, 1, v2
	s_mov_b32 s52, 0x3e38aa3b
	s_movk_i32 s53, 0x7b
	v_readlane_b32 s15, v255, 3
	v_readlane_b32 s54, v254, 44
	v_readlane_b32 s55, v254, 45
	v_readlane_b32 s56, v254, 46
	v_readlane_b32 s57, v254, 47
	v_readlane_b32 s58, v254, 48
	v_readlane_b32 s59, v254, 49
	v_readlane_b32 s60, v254, 50
	v_readlane_b32 s61, v254, 51
	v_readlane_b32 s62, v254, 52
	v_readlane_b32 s63, v254, 53
	v_readlane_b32 s64, v254, 54
	v_readlane_b32 s65, v254, 55
	v_readlane_b32 s66, v254, 56
	v_readlane_b32 s67, v254, 57
	v_mov_b32_e32 v56, v203
	v_mov_b32_e32 v57, v1
	v_lshl_add_u64 v[56:57], s[0:1], 0, v[56:57]
	global_load_dwordx2 v[52:53], v[56:57], off
	v_mov_b32_e32 v56, v202
	v_mov_b32_e32 v57, v1
	v_lshl_add_u64 v[56:57], s[0:1], 0, v[56:57]
	global_load_dwordx2 v[54:55], v[56:57], off
	s_waitcnt vmcnt(0)
	s_branch .LBB0_445

.LBB0_445:
	v_cmp_gt_u32_e64 s[44:45], 64, v11
	s_and_b64 s[28:29], s[20:21], s[44:45]
	v_cmp_lt_u32_e64 s[42:43], 63, v11
	s_xor_b64 s[34:35], s[28:29], -1
	s_and_saveexec_b64 s[28:29], s[34:35]
	s_cbranch_execz .LBB0_444
	v_and_b32_e32 v22, 63, v11
	s_andn2_b64 vcc, exec, s[4:5]
	s_mov_b64 s[34:35], -1
	s_cbranch_vccnz .LBB0_450
	v_cndmask_b32_e64 v6, v54, v52, s[44:45]
	v_cndmask_b32_e64 v7, v55, v53, s[44:45]
	v_readlane_b32 s34, v252, 36
	v_readlane_b32 s35, v252, 37
	v_or_b32_e32 v5, s76, v22
	v_and_b32_e32 v4, 0xfffffe00, v24
	v_mov_b64_e32 v[2:3], s[34:35]
	s_movk_i32 s34, 0xc00
	v_mad_u64_u32 v[2:3], s[34:35], v5, s34, v[2:3]
	v_ashrrev_i32_e32 v5, 31, v4
	v_lshl_add_u64 v[2:3], v[4:5], 1, v[2:3]
	v_lshlrev_b32_e32 v8, 1, v10
	v_mov_b32_e32 v9, v1
	v_lshl_add_u64 v[2:3], v[2:3], 0, v[0:1]
	v_lshl_add_u64 v[2:3], v[2:3], 0, v[8:9]
	global_load_dwordx4 v[2:5], v[2:3], off
	v_lshlrev_b32_e32 v8, 2, v10
	v_cmp_lt_i32_e32 vcc, v227, v221
	s_nop 0
	v_lshl_add_u64 v[6:7], s[12:13], 2, v[6:7]
	v_lshl_add_u64 v[26:27], v[6:7], 0, v[8:9]
	global_load_dwordx4 v[6:9], v[26:27], off
	s_nop 0
	global_load_dwordx4 v[26:29], v[26:27], off offset:16
	s_waitcnt vmcnt(2)
	v_cndmask_b32_e32 v23, v220, v227, vcc
	v_lshlrev_b32_e32 v23, 2, v23
	v_cmp_lt_i32_e32 vcc, v226, v221
	v_lshlrev_b32_e32 v30, 16, v2
	v_and_b32_e32 v31, 0xffff0000, v2
	v_lshlrev_b32_e32 v2, 16, v3
	v_and_b32_e32 v3, 0xffff0000, v3
	v_pk_mul_f32 v[36:37], v[30:31], v[30:31]
	v_pk_mul_f32 v[38:39], v[2:3], v[2:3]
	v_add_f32_e32 v25, v36, v37
	v_lshlrev_b32_e32 v32, 16, v4
	v_and_b32_e32 v33, 0xffff0000, v4
	v_add_f32_e32 v25, v25, v38
	v_pk_mul_f32 v[40:41], v[32:33], v[32:33]
	v_add_f32_e32 v25, v39, v25
	v_lshlrev_b32_e32 v35, 16, v5
	v_and_b32_e32 v34, 0xffff0000, v5
	v_add_f32_e32 v25, v40, v25
	v_pk_mul_f32 v[4:5], v[34:35], v[34:35]
	v_add_f32_e32 v25, v41, v25
	v_add_f32_e32 v5, v5, v25
	v_add_f32_e32 v4, v4, v5
	ds_bpermute_b32 v5, v23, v4
	v_cndmask_b32_e32 v23, v220, v226, vcc
	v_lshlrev_b32_e32 v23, 2, v23
	v_cmp_lt_i32_e32 vcc, v235, v221
	s_waitcnt lgkmcnt(0)
	v_add_f32_e32 v4, v4, v5
	ds_bpermute_b32 v5, v23, v4
	v_cndmask_b32_e32 v23, v220, v235, vcc
	v_lshlrev_b32_e32 v23, 2, v23
	s_waitcnt lgkmcnt(0)
	v_add_f32_e32 v4, v4, v5
	ds_bpermute_b32 v5, v23, v4
	s_waitcnt lgkmcnt(0)
	v_add_f32_e32 v4, v4, v5
	v_fmamk_f32 v4, v4, 0x3c800000, v187
	v_mul_f32_e32 v5, 0x4b800000, v4
	v_cmp_gt_f32_e32 vcc, s82, v4
	s_nop 1
	v_cndmask_b32_e32 v4, v4, v5, vcc
	v_rsq_f32_e32 v4, v4
	s_nop 0
	v_mul_f32_e32 v5, 0x45800000, v4
	v_cndmask_b32_e32 v4, v4, v5, vcc
	v_pk_mul_f32 v[30:31], v[4:5], v[30:31] op_sel_hi:[0,1]
	v_pk_mul_f32 v[36:37], v[4:5], v[2:3] op_sel_hi:[0,1]
	v_pk_mul_f32 v[32:33], v[4:5], v[32:33] op_sel_hi:[0,1]
	v_pk_mul_f32 v[34:35], v[4:5], v[34:35] op_sel_hi:[0,1]
	s_waitcnt vmcnt(1)
	v_pk_mul_f32 v[2:3], v[6:7], v[30:31]
	v_pk_mul_f32 v[4:5], v[8:9], v[36:37]
	s_waitcnt vmcnt(0)
	v_pk_mul_f32 v[6:7], v[26:27], v[32:33]
	v_pk_mul_f32 v[8:9], v[28:29], v[34:35] op_sel:[0,1] op_sel_hi:[1,0]
	s_cbranch_execz .LBB0_451
